# P1: waves 0-3 wait for waves 4-7 (end-of-tile re-sync barrier) a few stores into the epilogue instead of before it
# speedup vs baseline: 1.0044x; 1.0044x over previous
.Lmid_p1:
	s_add_i32 s60, 0, 0x18000
	s_add_i32 s61, 0, 0x1c000
	v_add_u32_e32 v92, s60, v173
	v_add_u32_e32 v152, s61, v173
	ds_read_b128 v[72:75], v92
	ds_read_b128 v[76:79], v92 offset:1024
	ds_read_b128 v[88:91], v92 offset:2048
	ds_read_b128 v[92:95], v92 offset:3072
	ds_read_b128 v[162:165], v152
	ds_read_b128 v[166:169], v152 offset:1024
	ds_read_b128 v[180:183], v152 offset:2048
	ds_read_b128 v[184:187], v152 offset:3072
	s_add_u32 s36, s36, 0x40000
	s_addc_u32 s37, s37, 0
	s_mov_b32 m0, s39
	v_lshl_add_u64 v[226:227], s[36:37], 0, v[144:145]
	ds_read_b128 v[188:191], v177 offset:32768
	ds_read_b128 v[192:195], v177 offset:33792
	ds_read_b128 v[198:201], v177 offset:34816
	ds_read_b128 v[202:205], v177 offset:35840
	ds_read_b128 v[206:209], v177 offset:36864
	ds_read_b128 v[210:213], v177 offset:37888
	ds_read_b128 v[214:217], v177 offset:38912
	ds_read_b128 v[218:221], v177 offset:39936
	global_load_lds_dwordx4 v[226:227], off
	v_lshl_add_u64 v[226:227], s[36:37], 0, v[148:149]
	s_mov_b32 m0, s40
	s_nop 0
	global_load_lds_dwordx4 v[226:227], off
	s_waitcnt vmcnt(8)
	s_waitcnt lgkmcnt(0)
	s_barrier
	s_setprio 1
	s_waitcnt lgkmcnt(0)
	v_mfma_f32_16x16x32_bf16 v[140:143], v[72:75], v[188:191], v[140:143]
	v_mfma_f32_16x16x32_bf16 v[136:139], v[88:91], v[188:191], v[136:139]
	v_mfma_f32_16x16x32_bf16 v[124:127], v[72:75], v[198:201], v[124:127]
	v_mfma_f32_16x16x32_bf16 v[120:123], v[88:91], v[198:201], v[120:123]
	v_mfma_f32_16x16x32_bf16 v[108:111], v[72:75], v[206:209], v[108:111]
	v_mfma_f32_16x16x32_bf16 v[104:107], v[88:91], v[206:209], v[104:107]
	v_mfma_f32_16x16x32_bf16 v[84:87], v[72:75], v[214:217], v[84:87]
	v_mfma_f32_16x16x32_bf16 v[80:83], v[88:91], v[214:217], v[80:83]
	v_mfma_f32_16x16x32_bf16 v[140:143], v[76:79], v[192:195], v[140:143]
	v_mfma_f32_16x16x32_bf16 v[136:139], v[92:95], v[192:195], v[136:139]
	v_mfma_f32_16x16x32_bf16 v[124:127], v[76:79], v[202:205], v[124:127]
	v_mfma_f32_16x16x32_bf16 v[120:123], v[92:95], v[202:205], v[120:123]
	v_mfma_f32_16x16x32_bf16 v[108:111], v[76:79], v[210:213], v[108:111]
	v_mfma_f32_16x16x32_bf16 v[104:107], v[92:95], v[210:213], v[104:107]
	v_mfma_f32_16x16x32_bf16 v[84:87], v[76:79], v[218:221], v[84:87]
	v_mfma_f32_16x16x32_bf16 v[80:83], v[92:95], v[218:221], v[80:83]
	s_setprio 0
	s_setprio 1
	v_mfma_f32_16x16x32_bf16 v[132:135], v[162:165], v[188:191], v[132:135]
	v_mfma_f32_16x16x32_bf16 v[128:131], v[180:183], v[188:191], v[128:131]
	v_mfma_f32_16x16x32_bf16 v[116:119], v[162:165], v[198:201], v[116:119]
	v_mfma_f32_16x16x32_bf16 v[112:115], v[180:183], v[198:201], v[112:115]
	v_mfma_f32_16x16x32_bf16 v[100:103], v[162:165], v[206:209], v[100:103]
	v_mfma_f32_16x16x32_bf16 v[96:99], v[180:183], v[206:209], v[96:99]
	v_mfma_f32_16x16x32_bf16 v[68:71], v[162:165], v[214:217], v[68:71]
	v_mfma_f32_16x16x32_bf16 v[64:67], v[180:183], v[214:217], v[64:67]
	v_mfma_f32_16x16x32_bf16 v[132:135], v[166:169], v[192:195], v[132:135]
	v_mfma_f32_16x16x32_bf16 v[128:131], v[184:187], v[192:195], v[128:131]
	v_mfma_f32_16x16x32_bf16 v[116:119], v[166:169], v[202:205], v[116:119]
	v_mfma_f32_16x16x32_bf16 v[112:115], v[184:187], v[202:205], v[112:115]
	v_mfma_f32_16x16x32_bf16 v[100:103], v[166:169], v[210:213], v[100:103]
	v_mfma_f32_16x16x32_bf16 v[96:99], v[184:187], v[210:213], v[96:99]
	v_mfma_f32_16x16x32_bf16 v[68:71], v[166:169], v[218:221], v[68:71]
	v_mfma_f32_16x16x32_bf16 v[64:67], v[184:187], v[218:221], v[64:67]
	s_setprio 0
	s_barrier
	s_add_i32 s36, s60, s33
	v_lshl_add_u64 v[170:171], v[170:171], 0, s[18:19]
	s_mov_b32 m0, s36
	ds_read_b128 v[188:191], v177 offset:49152
	ds_read_b128 v[192:195], v177 offset:50176
	ds_read_b128 v[198:201], v177 offset:51200
	ds_read_b128 v[202:205], v177 offset:52224
	ds_read_b128 v[206:209], v177 offset:53248
	ds_read_b128 v[210:213], v177 offset:54272
	ds_read_b128 v[214:217], v177 offset:55296
	ds_read_b128 v[218:221], v177 offset:56320
	global_load_lds_dwordx4 v[170:171], off
	s_add_i32 m0, s36, 0x2000
	s_add_u32 s34, s34, 0x40080
	v_lshl_add_u64 v[170:171], v[196:197], 0, s[18:19]
	s_addc_u32 s35, s35, 0
	s_add_i32 s36, s61, s33
	global_load_lds_dwordx4 v[170:171], off
	v_lshl_add_u64 v[170:171], s[34:35], 0, v[146:147]
	s_mov_b32 m0, s36
	s_nop 0
	global_load_lds_dwordx4 v[170:171], off
	v_lshl_add_u64 v[170:171], s[34:35], 0, v[150:151]
	s_add_i32 m0, s36, 0x2000
	s_nop 0
	global_load_lds_dwordx4 v[170:171], off
	v_lshl_add_u64 v[170:171], v[222:223], 0, s[18:19]
	s_mov_b32 m0, s42
	s_nop 0
	global_load_lds_dwordx4 v[170:171], off
	v_lshl_add_u64 v[170:171], v[224:225], 0, s[18:19]
	s_mov_b32 m0, s43
	s_nop 0
	global_load_lds_dwordx4 v[170:171], off
	s_waitcnt vmcnt(8)
	s_waitcnt lgkmcnt(0)
	s_barrier
	s_setprio 1
	s_waitcnt lgkmcnt(0)
	v_mfma_f32_16x16x32_bf16 v[60:63], v[72:75], v[188:191], v[60:63]
	v_mfma_f32_16x16x32_bf16 v[56:59], v[88:91], v[188:191], v[56:59]
	v_mfma_f32_16x16x32_bf16 v[44:47], v[72:75], v[198:201], v[44:47]
	v_mfma_f32_16x16x32_bf16 v[40:43], v[88:91], v[198:201], v[40:43]
	v_mfma_f32_16x16x32_bf16 v[28:31], v[72:75], v[206:209], v[28:31]
	v_mfma_f32_16x16x32_bf16 v[24:27], v[88:91], v[206:209], v[24:27]
	v_mfma_f32_16x16x32_bf16 v[12:15], v[72:75], v[214:217], v[12:15]
	v_mfma_f32_16x16x32_bf16 v[8:11], v[88:91], v[214:217], v[8:11]
	v_mfma_f32_16x16x32_bf16 v[60:63], v[76:79], v[192:195], v[60:63]
	v_mfma_f32_16x16x32_bf16 v[56:59], v[92:95], v[192:195], v[56:59]
	v_mfma_f32_16x16x32_bf16 v[44:47], v[76:79], v[202:205], v[44:47]
	v_mfma_f32_16x16x32_bf16 v[40:43], v[92:95], v[202:205], v[40:43]
	v_mfma_f32_16x16x32_bf16 v[28:31], v[76:79], v[210:213], v[28:31]
	v_mfma_f32_16x16x32_bf16 v[24:27], v[92:95], v[210:213], v[24:27]
	v_mfma_f32_16x16x32_bf16 v[12:15], v[76:79], v[218:221], v[12:15]
	v_mfma_f32_16x16x32_bf16 v[8:11], v[92:95], v[218:221], v[8:11]
	s_setprio 0
	s_setprio 1
	v_mfma_f32_16x16x32_bf16 v[52:55], v[162:165], v[188:191], v[52:55]
	v_mfma_f32_16x16x32_bf16 v[48:51], v[180:183], v[188:191], v[48:51]
	v_mfma_f32_16x16x32_bf16 v[36:39], v[162:165], v[198:201], v[36:39]
	v_mfma_f32_16x16x32_bf16 v[32:35], v[180:183], v[198:201], v[32:35]
	v_mfma_f32_16x16x32_bf16 v[20:23], v[162:165], v[206:209], v[20:23]
	v_mfma_f32_16x16x32_bf16 v[16:19], v[180:183], v[206:209], v[16:19]
	v_mfma_f32_16x16x32_bf16 v[4:7], v[162:165], v[214:217], v[4:7]
	v_mfma_f32_16x16x32_bf16 v[0:3], v[180:183], v[214:217], v[0:3]
	v_mfma_f32_16x16x32_bf16 v[52:55], v[166:169], v[192:195], v[52:55]
	v_mfma_f32_16x16x32_bf16 v[48:51], v[184:187], v[192:195], v[48:51]
	v_mfma_f32_16x16x32_bf16 v[36:39], v[166:169], v[202:205], v[36:39]
	v_mfma_f32_16x16x32_bf16 v[32:35], v[184:187], v[202:205], v[32:35]
	v_mfma_f32_16x16x32_bf16 v[20:23], v[166:169], v[210:213], v[20:23]
	v_mfma_f32_16x16x32_bf16 v[16:19], v[184:187], v[210:213], v[16:19]
	v_mfma_f32_16x16x32_bf16 v[4:7], v[166:169], v[218:221], v[4:7]
	v_mfma_f32_16x16x32_bf16 v[0:3], v[184:187], v[218:221], v[0:3]
	s_setprio 0
	s_barrier
	s_add_i32 s59, s59, 2
	s_add_u32 s30, s30, 0x100
	s_addc_u32 s31, s31, 0
	s_add_u32 s57, s57, 0x100
	s_addc_u32 s58, s58, 0
	s_cmp_gt_u32 s59, 13
	s_cbranch_scc0 .LBB0_120
	s_and_b64 vcc, exec, s[20:21]
	s_cbranch_vccz .LBB0_123
.LBB0_123:
	s_lshl_b32 s5, s4, 8
	s_and_b32 s7, s4, -2
	s_cmp_lg_u32 s7, 10
	s_cbranch_scc1 .LBB0_134
	v_fma_f32 v72, v140, v140, 0
	v_fmac_f32_e32 v72, v141, v141
	v_fmac_f32_e32 v72, v142, v142
	v_fmac_f32_e32 v72, v143, v143
	v_fmac_f32_e32 v72, v136, v136
	v_fma_f32 v73, v132, v132, 0
	v_fmac_f32_e32 v72, v137, v137
	v_fmac_f32_e32 v73, v133, v133
	v_fmac_f32_e32 v72, v138, v138
	v_fmac_f32_e32 v73, v134, v134
	v_fmac_f32_e32 v72, v139, v139
	v_fmac_f32_e32 v73, v135, v135
	v_mov_b32_e32 v74, v72
	v_fmac_f32_e32 v73, v128, v128
	s_nop 0
	v_permlane16_swap_b32_e32 v72, v74
	v_fmac_f32_e32 v73, v129, v129
	v_add_f32_e32 v72, v72, v74
	v_fmac_f32_e32 v73, v130, v130
	v_mov_b32_e32 v74, v72
	v_fmac_f32_e32 v73, v131, v131
	s_nop 0
	v_permlane32_swap_b32_e32 v72, v74
	v_add_f32_e32 v72, v72, v74
	v_mov_b32_e32 v74, v73
	s_nop 1
	v_permlane16_swap_b32_e32 v73, v74
	v_add_f32_e32 v73, v73, v74
	v_mov_b32_e32 v74, v73
	s_nop 1
	v_permlane32_swap_b32_e32 v73, v74
	v_add_f32_e32 v73, v73, v74
	v_fma_f32 v74, v124, v124, 0
	v_fmac_f32_e32 v74, v125, v125
	v_fmac_f32_e32 v74, v126, v126
	v_fmac_f32_e32 v74, v127, v127
	v_fmac_f32_e32 v74, v120, v120
	v_fma_f32 v75, v116, v116, 0
	v_fmac_f32_e32 v74, v121, v121
	v_fmac_f32_e32 v75, v117, v117
	v_fmac_f32_e32 v74, v122, v122
	v_fmac_f32_e32 v75, v118, v118
	v_fmac_f32_e32 v74, v123, v123
	v_fmac_f32_e32 v75, v119, v119
	v_mov_b32_e32 v76, v74
	v_fmac_f32_e32 v75, v112, v112
	s_nop 0
	v_permlane16_swap_b32_e32 v74, v76
	v_fmac_f32_e32 v75, v113, v113
	v_add_f32_e32 v74, v74, v76
	v_fmac_f32_e32 v75, v114, v114
	v_mov_b32_e32 v76, v74
	v_fmac_f32_e32 v75, v115, v115
	s_nop 0
	v_permlane32_swap_b32_e32 v74, v76
	v_add_f32_e32 v74, v74, v76
	v_mov_b32_e32 v76, v75
	s_nop 1
	v_permlane16_swap_b32_e32 v75, v76
	v_max3_f32 v72, v72, 0, v74
	v_fma_f32 v74, v108, v108, 0
	v_add_f32_e32 v75, v75, v76
	v_fmac_f32_e32 v74, v109, v109
	v_mov_b32_e32 v76, v75
	v_fmac_f32_e32 v74, v110, v110
	s_nop 0
	v_permlane32_swap_b32_e32 v75, v76
	v_fmac_f32_e32 v74, v111, v111
	v_add_f32_e32 v75, v75, v76
	v_fmac_f32_e32 v74, v104, v104
	v_max3_f32 v73, v73, 0, v75
	v_fma_f32 v75, v100, v100, 0
	v_fmac_f32_e32 v74, v105, v105
	v_fmac_f32_e32 v75, v101, v101
	v_fmac_f32_e32 v74, v106, v106
	v_fmac_f32_e32 v75, v102, v102
	v_fmac_f32_e32 v74, v107, v107
	v_fmac_f32_e32 v75, v103, v103
	v_mov_b32_e32 v76, v74
	v_fmac_f32_e32 v75, v96, v96
	s_nop 0
	v_permlane16_swap_b32_e32 v74, v76
	v_fmac_f32_e32 v75, v97, v97
	v_add_f32_e32 v74, v74, v76
	v_fmac_f32_e32 v75, v98, v98
	v_mov_b32_e32 v76, v74
	v_fmac_f32_e32 v75, v99, v99
	s_nop 0
	v_permlane32_swap_b32_e32 v74, v76
	v_add_f32_e32 v74, v74, v76
	v_mov_b32_e32 v76, v75
	s_nop 1
	v_permlane16_swap_b32_e32 v75, v76
	v_add_f32_e32 v75, v75, v76
	v_mov_b32_e32 v76, v75
	s_nop 1
	v_permlane32_swap_b32_e32 v75, v76
	v_add_f32_e32 v75, v75, v76
	v_fma_f32 v76, v84, v84, 0
	v_fmac_f32_e32 v76, v85, v85
	v_fmac_f32_e32 v76, v86, v86
	v_fmac_f32_e32 v76, v87, v87
	v_fmac_f32_e32 v76, v80, v80
	v_fma_f32 v77, v68, v68, 0
	v_fmac_f32_e32 v76, v81, v81
	v_fmac_f32_e32 v77, v69, v69
	v_fmac_f32_e32 v76, v82, v82
	v_fmac_f32_e32 v77, v70, v70
	v_fmac_f32_e32 v76, v83, v83
	v_fmac_f32_e32 v77, v71, v71
	v_mov_b32_e32 v78, v76
	v_fmac_f32_e32 v77, v64, v64
	s_nop 0
	v_permlane16_swap_b32_e32 v76, v78
	v_fmac_f32_e32 v77, v65, v65
	v_add_f32_e32 v76, v76, v78
	v_fmac_f32_e32 v77, v66, v66
	v_mov_b32_e32 v78, v76
	v_fmac_f32_e32 v77, v67, v67
	s_nop 0
	v_permlane32_swap_b32_e32 v76, v78
	v_add_f32_e32 v76, v76, v78
	v_mov_b32_e32 v78, v77
	s_nop 1
	v_permlane16_swap_b32_e32 v77, v78
	v_max3_f32 v72, v72, v74, v76
	v_fma_f32 v74, v60, v60, 0
	v_add_f32_e32 v77, v77, v78
	v_fmac_f32_e32 v74, v61, v61
	v_mov_b32_e32 v78, v77
	v_fmac_f32_e32 v74, v62, v62
	s_nop 0
	v_permlane32_swap_b32_e32 v77, v78
	v_fmac_f32_e32 v74, v63, v63
	v_add_f32_e32 v77, v77, v78
	v_fmac_f32_e32 v74, v56, v56
	v_max3_f32 v73, v73, v75, v77
	v_fma_f32 v75, v52, v52, 0
	v_fmac_f32_e32 v74, v57, v57
	v_fmac_f32_e32 v75, v53, v53
	v_fmac_f32_e32 v74, v58, v58
	v_fmac_f32_e32 v75, v54, v54
	v_fmac_f32_e32 v74, v59, v59
	v_fmac_f32_e32 v75, v55, v55
	v_mov_b32_e32 v76, v74
	v_fmac_f32_e32 v75, v48, v48
	s_nop 0
	v_permlane16_swap_b32_e32 v74, v76
	v_fmac_f32_e32 v75, v49, v49
	v_add_f32_e32 v74, v74, v76
	v_fmac_f32_e32 v75, v50, v50
	v_mov_b32_e32 v76, v74
	v_fmac_f32_e32 v75, v51, v51
	s_nop 0
	v_permlane32_swap_b32_e32 v74, v76
	v_add_f32_e32 v74, v74, v76
	v_mov_b32_e32 v76, v75
	s_nop 1
	v_permlane16_swap_b32_e32 v75, v76
	v_add_f32_e32 v75, v75, v76
	v_mov_b32_e32 v76, v75
	s_nop 1
	v_permlane32_swap_b32_e32 v75, v76
	v_add_f32_e32 v75, v75, v76
	v_fma_f32 v76, v44, v44, 0
	v_fmac_f32_e32 v76, v45, v45
	v_fmac_f32_e32 v76, v46, v46
	v_fmac_f32_e32 v76, v47, v47
	v_fmac_f32_e32 v76, v40, v40
	v_fma_f32 v77, v36, v36, 0
	v_fmac_f32_e32 v76, v41, v41
	v_fmac_f32_e32 v77, v37, v37
	v_fmac_f32_e32 v76, v42, v42
	v_fmac_f32_e32 v77, v38, v38
	v_fmac_f32_e32 v76, v43, v43
	v_fmac_f32_e32 v77, v39, v39
	v_mov_b32_e32 v78, v76
	v_fmac_f32_e32 v77, v32, v32
	s_nop 0
	v_permlane16_swap_b32_e32 v76, v78
	v_fmac_f32_e32 v77, v33, v33
	v_add_f32_e32 v76, v76, v78
	v_fmac_f32_e32 v77, v34, v34
	v_mov_b32_e32 v78, v76
	v_fmac_f32_e32 v77, v35, v35
	s_nop 0
	v_permlane32_swap_b32_e32 v76, v78
	v_add_f32_e32 v76, v76, v78
	v_mov_b32_e32 v78, v77
	s_nop 1
	v_permlane16_swap_b32_e32 v77, v78
	v_max3_f32 v72, v72, v74, v76
	v_fma_f32 v74, v28, v28, 0
	v_add_f32_e32 v77, v77, v78
	v_fmac_f32_e32 v74, v29, v29
	v_mov_b32_e32 v78, v77
	v_fmac_f32_e32 v74, v30, v30
	s_nop 0
	v_permlane32_swap_b32_e32 v77, v78
	v_fmac_f32_e32 v74, v31, v31
	v_add_f32_e32 v77, v77, v78
	v_fmac_f32_e32 v74, v24, v24
	v_max3_f32 v73, v73, v75, v77
	v_fma_f32 v75, v20, v20, 0
	v_fmac_f32_e32 v74, v25, v25
	v_fmac_f32_e32 v75, v21, v21
	v_fmac_f32_e32 v74, v26, v26
	v_fmac_f32_e32 v75, v22, v22
	v_fmac_f32_e32 v74, v27, v27
	v_fmac_f32_e32 v75, v23, v23
	v_mov_b32_e32 v76, v74
	v_fmac_f32_e32 v75, v16, v16
	s_nop 0
	v_permlane16_swap_b32_e32 v74, v76
	v_fmac_f32_e32 v75, v17, v17
	v_add_f32_e32 v74, v74, v76
	v_fmac_f32_e32 v75, v18, v18
	v_mov_b32_e32 v76, v74
	v_fmac_f32_e32 v75, v19, v19
	s_nop 0
	v_permlane32_swap_b32_e32 v74, v76
	v_add_f32_e32 v74, v74, v76
	v_mov_b32_e32 v76, v75
	s_nop 1
	v_permlane16_swap_b32_e32 v75, v76
	v_add_f32_e32 v75, v75, v76
	v_mov_b32_e32 v76, v75
	s_nop 1
	v_permlane32_swap_b32_e32 v75, v76
	v_add_f32_e32 v75, v75, v76
	v_fma_f32 v76, v12, v12, 0
	v_fmac_f32_e32 v76, v13, v13
	v_fmac_f32_e32 v76, v14, v14
	v_fmac_f32_e32 v76, v15, v15
	v_fmac_f32_e32 v76, v8, v8
	v_fmac_f32_e32 v76, v9, v9
	v_fmac_f32_e32 v76, v10, v10
	v_fmac_f32_e32 v76, v11, v11
	v_fma_f32 v77, v4, v4, 0
	v_mov_b32_e32 v78, v76
	v_fmac_f32_e32 v77, v5, v5
	s_nop 0
	v_permlane16_swap_b32_e32 v76, v78
	v_fmac_f32_e32 v77, v6, v6
	v_add_f32_e32 v76, v76, v78
	v_fmac_f32_e32 v77, v7, v7
	v_mov_b32_e32 v78, v76
	v_fmac_f32_e32 v77, v0, v0
	s_nop 0
	v_permlane32_swap_b32_e32 v76, v78
	v_fmac_f32_e32 v77, v1, v1
	v_add_f32_e32 v76, v76, v78
	v_fmac_f32_e32 v77, v2, v2
	v_max3_f32 v72, v72, v74, v76
	v_fmac_f32_e32 v77, v3, v3
	v_mov_b32_e32 v78, v77
	v_mov_b32_dpp v74, v72 row_shr:1 row_mask:0xf bank_mask:0xf bound_ctrl:1
	v_max_f32_e32 v74, v74, v74
	v_permlane16_swap_b32_e32 v77, v78
	v_max_f32_e32 v72, v72, v74
	v_add_f32_e32 v77, v77, v78
	v_mov_b32_e32 v78, v77
	v_mov_b32_dpp v74, v72 row_shr:2 row_mask:0xf bank_mask:0xf bound_ctrl:1
	v_max_f32_e32 v74, v74, v74
	v_permlane32_swap_b32_e32 v77, v78
	v_max_f32_e32 v72, v72, v74
	v_add_f32_e32 v77, v77, v78
	v_max3_f32 v73, v73, v75, v77
	v_mov_b32_dpp v74, v72 row_shr:4 row_mask:0xf bank_mask:0xf bound_ctrl:1
	v_max_f32_e32 v74, v74, v74
	v_max_f32_e32 v74, v72, v74
	v_mov_b32_dpp v72, v73 row_shr:1 row_mask:0xf bank_mask:0xf bound_ctrl:1
	v_max_f32_e32 v72, v72, v72
	v_max_f32_e32 v72, v73, v72
	v_mov_b32_dpp v75, v74 row_shr:8 row_mask:0xf bank_mask:0xf bound_ctrl:1
	s_nop 0
	v_mov_b32_dpp v73, v72 row_shr:2 row_mask:0xf bank_mask:0xf bound_ctrl:1
	v_max_f32_e32 v73, v73, v73
	v_max_f32_e32 v72, v72, v73
	s_nop 1
	v_mov_b32_dpp v73, v72 row_shr:4 row_mask:0xf bank_mask:0xf bound_ctrl:1
	v_max_f32_e32 v73, v73, v73
	v_max_f32_e32 v72, v72, v73
	s_nop 1
	v_mov_b32_dpp v73, v72 row_shr:8 row_mask:0xf bank_mask:0xf bound_ctrl:1
	s_and_saveexec_b64 s[30:31], s[0:1]
	s_cbranch_execz .LBB0_133
	v_max_f32_e32 v75, v75, v75
	v_max_f32_e32 v74, v74, v74
	s_mov_b64 s[34:35], exec
	v_max_f32_e32 v74, v74, v75
	s_mov_b32 s7, 0

.Lp1e_projc:
	s_add_u32 s30, s78, s30
	s_addc_u32 s31, s79, 0
	s_mov_b32 s35, 0x80000
	v_and_b32_e32 v152, 15, v231
	v_lshrrev_b32_e32 v162, 4, v231
	v_lshlrev_b32_e32 v152, s34, v152
	s_lshl_b32 s23, 16, s34
	v_lshl_or_b32 v152, v162, 4, v152
	s_lshl_b32 s4, s23, 1
	s_add_u32 s6, s4, s23
	s_lshl_b32 s5, 0x80, s34
	v_add_u32_e32 v162, s23, v152
	v_add_u32_e32 v163, s4, v152
	v_add_u32_e32 v164, s6, v152
	v_cvt_pk_bf16_f32 v140, v140, v141
	v_cvt_pk_bf16_f32 v141, v142, v143
	v_cvt_pk_bf16_f32 v142, v136, v137
	v_cvt_pk_bf16_f32 v143, v138, v139
	global_store_dwordx4 v152, v[140:143], s[30:31]
	v_cvt_pk_bf16_f32 v124, v124, v125
	v_cvt_pk_bf16_f32 v125, v126, v127
	v_cvt_pk_bf16_f32 v126, v120, v121
	v_cvt_pk_bf16_f32 v127, v122, v123
	global_store_dwordx4 v162, v[124:127], s[30:31]
	v_cvt_pk_bf16_f32 v108, v108, v109
	v_cvt_pk_bf16_f32 v109, v110, v111
	v_cvt_pk_bf16_f32 v110, v104, v105
	v_cvt_pk_bf16_f32 v111, v106, v107
	global_store_dwordx4 v163, v[108:111], s[30:31]
	v_cvt_pk_bf16_f32 v84, v84, v85
	v_cvt_pk_bf16_f32 v85, v86, v87
	v_cvt_pk_bf16_f32 v86, v80, v81
	v_cvt_pk_bf16_f32 v87, v82, v83
	global_store_dwordx4 v164, v[84:87], s[30:31]
	s_and_b64 vcc, exec, s[20:21]
	s_cbranch_vccz .Lp1e_noxp
	s_barrier
.Lp1e_noxp:
	s_add_u32 s30, s30, s35
	s_addc_u32 s31, s31, 0
	v_cvt_pk_bf16_f32 v132, v132, v133
	v_cvt_pk_bf16_f32 v133, v134, v135
	v_cvt_pk_bf16_f32 v134, v128, v129
	v_cvt_pk_bf16_f32 v135, v130, v131
	global_store_dwordx4 v152, v[132:135], s[30:31]
	v_cvt_pk_bf16_f32 v116, v116, v117
	v_cvt_pk_bf16_f32 v117, v118, v119
	v_cvt_pk_bf16_f32 v118, v112, v113
	v_cvt_pk_bf16_f32 v119, v114, v115
	global_store_dwordx4 v162, v[116:119], s[30:31]
	v_cvt_pk_bf16_f32 v100, v100, v101
	v_cvt_pk_bf16_f32 v101, v102, v103
	v_cvt_pk_bf16_f32 v102, v96, v97
	v_cvt_pk_bf16_f32 v103, v98, v99
	global_store_dwordx4 v163, v[100:103], s[30:31]
	v_cvt_pk_bf16_f32 v68, v68, v69
	v_cvt_pk_bf16_f32 v69, v70, v71
	v_cvt_pk_bf16_f32 v70, v64, v65
	v_cvt_pk_bf16_f32 v71, v66, v67
	global_store_dwordx4 v164, v[68:71], s[30:31]
	s_sub_u32 s30, s30, s35
	s_subb_u32 s31, s31, 0
	s_add_u32 s30, s30, s5
	s_addc_u32 s31, s31, 0
	v_cvt_pk_bf16_f32 v60, v60, v61
	v_cvt_pk_bf16_f32 v61, v62, v63
	v_cvt_pk_bf16_f32 v62, v56, v57
	v_cvt_pk_bf16_f32 v63, v58, v59
	global_store_dwordx4 v152, v[60:63], s[30:31]
	v_cvt_pk_bf16_f32 v44, v44, v45
	v_cvt_pk_bf16_f32 v45, v46, v47
	v_cvt_pk_bf16_f32 v46, v40, v41
	v_cvt_pk_bf16_f32 v47, v42, v43
	global_store_dwordx4 v162, v[44:47], s[30:31]
	v_cvt_pk_bf16_f32 v28, v28, v29
	v_cvt_pk_bf16_f32 v29, v30, v31
	v_cvt_pk_bf16_f32 v30, v24, v25
	v_cvt_pk_bf16_f32 v31, v26, v27
	global_store_dwordx4 v163, v[28:31], s[30:31]
	v_cvt_pk_bf16_f32 v12, v12, v13
	v_cvt_pk_bf16_f32 v13, v14, v15
	v_cvt_pk_bf16_f32 v14, v8, v9
	v_cvt_pk_bf16_f32 v15, v10, v11
	global_store_dwordx4 v164, v[12:15], s[30:31]
	s_add_u32 s30, s30, s35
	s_addc_u32 s31, s31, 0
	v_cvt_pk_bf16_f32 v52, v52, v53
	v_cvt_pk_bf16_f32 v53, v54, v55
	v_cvt_pk_bf16_f32 v54, v48, v49
	v_cvt_pk_bf16_f32 v55, v50, v51
	global_store_dwordx4 v152, v[52:55], s[30:31]
	v_cvt_pk_bf16_f32 v36, v36, v37
	v_cvt_pk_bf16_f32 v37, v38, v39
	v_cvt_pk_bf16_f32 v38, v32, v33
	v_cvt_pk_bf16_f32 v39, v34, v35
	global_store_dwordx4 v162, v[36:39], s[30:31]
	v_cvt_pk_bf16_f32 v20, v20, v21
	v_cvt_pk_bf16_f32 v21, v22, v23
	v_cvt_pk_bf16_f32 v22, v16, v17
	v_cvt_pk_bf16_f32 v23, v18, v19
	global_store_dwordx4 v163, v[20:23], s[30:31]
	v_cvt_pk_bf16_f32 v4, v4, v5
	v_cvt_pk_bf16_f32 v5, v6, v7
	v_cvt_pk_bf16_f32 v6, v0, v1
	v_cvt_pk_bf16_f32 v7, v2, v3
	global_store_dwordx4 v164, v[4:7], s[30:31]
	s_branch .Lp1e_done
.Lp1e_gates:
	s_lshl_b32 s30, s6, 8
	s_lshl_b32 s31, s5, 6
	s_add_u32 s30, s30, s31
	s_lshl_b32 s30, s30, 12
	s_sub_u32 s31, s4, 16
	s_lshl_b32 s31, s31, 9
	s_lshl_b32 s23, s7, 6
	s_add_u32 s31, s31, s23
	s_lshl_b32 s23, s31, 1
	s_add_u32 s23, s23, s53
	s_add_u32 s30, s30, s31
	v_lshrrev_b32_e32 v165, 4, v231
	s_add_u32 s30, s74, s30
	s_addc_u32 s31, s75, 0
	v_lshl_add_u32 v165, v165, 5, s23
	s_mov_b32 s34, 12
	s_mov_b32 s35, 0x100
	ds_read_b128 v[92:95], v165
	ds_read_b128 v[88:91], v165 offset:16
	ds_read_b128 v[76:79], v165 offset:512
	ds_read_b128 v[72:75], v165 offset:528
	v_and_b32_e32 v152, 15, v231
	v_lshrrev_b32_e32 v162, 4, v231
	v_lshlrev_b32_e32 v152, s34, v152
	s_lshl_b32 s23, 16, s34
	v_lshl_or_b32 v152, v162, 4, v152
	s_lshl_b32 s4, s23, 1
	s_add_u32 s6, s4, s23
	s_lshl_b32 s5, 0x80, s34
	v_add_u32_e32 v162, s23, v152
	v_add_u32_e32 v163, s4, v152
	v_add_u32_e32 v164, s6, v152
	s_waitcnt lgkmcnt(0)
	v_pk_add_f32 v[140:141], v[140:141], v[92:93]
	v_pk_add_f32 v[142:143], v[142:143], v[94:95]
	v_pk_add_f32 v[136:137], v[136:137], v[88:89]
	v_pk_add_f32 v[138:139], v[138:139], v[90:91]
	v_mul_f32_e32 v140, 0xbfb8aa3b, v140
	v_mul_f32_e32 v141, 0xbfb8aa3b, v141
	v_mul_f32_e32 v142, 0xbfb8aa3b, v142
	v_mul_f32_e32 v143, 0xbfb8aa3b, v143
	v_mul_f32_e32 v136, 0xbfb8aa3b, v136
	v_mul_f32_e32 v137, 0xbfb8aa3b, v137
	v_mul_f32_e32 v138, 0xbfb8aa3b, v138
	v_mul_f32_e32 v139, 0xbfb8aa3b, v139
	v_exp_f32_e32 v140, v140
	v_exp_f32_e32 v141, v141
	v_exp_f32_e32 v142, v142
	v_exp_f32_e32 v143, v143
	v_exp_f32_e32 v136, v136
	v_exp_f32_e32 v137, v137
	v_exp_f32_e32 v138, v138
	v_exp_f32_e32 v139, v139
	v_add_f32_e32 v140, 1.0, v140
	v_add_f32_e32 v141, 1.0, v141
	v_add_f32_e32 v142, 1.0, v142
	v_add_f32_e32 v143, 1.0, v143
	v_add_f32_e32 v136, 1.0, v136
	v_add_f32_e32 v137, 1.0, v137
	v_add_f32_e32 v138, 1.0, v138
	v_add_f32_e32 v139, 1.0, v139
	v_rcp_f32_e32 v140, v140
	v_rcp_f32_e32 v141, v141
	v_rcp_f32_e32 v142, v142
	v_rcp_f32_e32 v143, v143
	v_rcp_f32_e32 v136, v136
	v_rcp_f32_e32 v137, v137
	v_rcp_f32_e32 v138, v138
	v_rcp_f32_e32 v139, v139
	s_nop 0
	v_cvt_pk_bf16_f32 v140, v140, v141
	v_cvt_pk_bf16_f32 v141, v142, v143
	v_cvt_pk_bf16_f32 v142, v136, v137
	v_cvt_pk_bf16_f32 v143, v138, v139
	global_store_dwordx4 v152, v[140:143], s[30:31] sc1
	s_and_b64 vcc, exec, s[20:21]
	s_cbranch_vccz .Lp1e_noxg
	s_barrier
.Lp1e_noxg:
	v_pk_add_f32 v[124:125], v[124:125], v[92:93]
	v_pk_add_f32 v[126:127], v[126:127], v[94:95]
	v_pk_add_f32 v[120:121], v[120:121], v[88:89]
	v_pk_add_f32 v[122:123], v[122:123], v[90:91]
	v_mul_f32_e32 v124, 0xbfb8aa3b, v124
	v_mul_f32_e32 v125, 0xbfb8aa3b, v125
	v_mul_f32_e32 v126, 0xbfb8aa3b, v126
	v_mul_f32_e32 v127, 0xbfb8aa3b, v127
	v_mul_f32_e32 v120, 0xbfb8aa3b, v120
	v_mul_f32_e32 v121, 0xbfb8aa3b, v121
	v_mul_f32_e32 v122, 0xbfb8aa3b, v122
	v_mul_f32_e32 v123, 0xbfb8aa3b, v123
	v_exp_f32_e32 v124, v124
	v_exp_f32_e32 v125, v125
	v_exp_f32_e32 v126, v126
	v_exp_f32_e32 v127, v127
	v_exp_f32_e32 v120, v120
	v_exp_f32_e32 v121, v121
	v_exp_f32_e32 v122, v122
	v_exp_f32_e32 v123, v123
	v_add_f32_e32 v124, 1.0, v124
	v_add_f32_e32 v125, 1.0, v125
	v_add_f32_e32 v126, 1.0, v126
	v_add_f32_e32 v127, 1.0, v127
	v_add_f32_e32 v120, 1.0, v120
	v_add_f32_e32 v121, 1.0, v121
	v_add_f32_e32 v122, 1.0, v122
	v_add_f32_e32 v123, 1.0, v123
	v_rcp_f32_e32 v124, v124
	v_rcp_f32_e32 v125, v125
	v_rcp_f32_e32 v126, v126
	v_rcp_f32_e32 v127, v127
	v_rcp_f32_e32 v120, v120
	v_rcp_f32_e32 v121, v121
	v_rcp_f32_e32 v122, v122
	v_rcp_f32_e32 v123, v123
	s_nop 0
	v_cvt_pk_bf16_f32 v124, v124, v125
	v_cvt_pk_bf16_f32 v125, v126, v127
	v_cvt_pk_bf16_f32 v126, v120, v121
	v_cvt_pk_bf16_f32 v127, v122, v123
	global_store_dwordx4 v162, v[124:127], s[30:31] sc1
	v_pk_add_f32 v[108:109], v[108:109], v[92:93]
	v_pk_add_f32 v[110:111], v[110:111], v[94:95]
	v_pk_add_f32 v[104:105], v[104:105], v[88:89]
	v_pk_add_f32 v[106:107], v[106:107], v[90:91]
	v_mul_f32_e32 v108, 0xbfb8aa3b, v108
	v_mul_f32_e32 v109, 0xbfb8aa3b, v109
	v_mul_f32_e32 v110, 0xbfb8aa3b, v110
	v_mul_f32_e32 v111, 0xbfb8aa3b, v111
	v_mul_f32_e32 v104, 0xbfb8aa3b, v104
	v_mul_f32_e32 v105, 0xbfb8aa3b, v105
	v_mul_f32_e32 v106, 0xbfb8aa3b, v106
	v_mul_f32_e32 v107, 0xbfb8aa3b, v107
	v_exp_f32_e32 v108, v108
	v_exp_f32_e32 v109, v109
	v_exp_f32_e32 v110, v110
	v_exp_f32_e32 v111, v111
	v_exp_f32_e32 v104, v104
	v_exp_f32_e32 v105, v105
	v_exp_f32_e32 v106, v106
	v_exp_f32_e32 v107, v107
	v_add_f32_e32 v108, 1.0, v108
	v_add_f32_e32 v109, 1.0, v109
	v_add_f32_e32 v110, 1.0, v110
	v_add_f32_e32 v111, 1.0, v111
	v_add_f32_e32 v104, 1.0, v104
	v_add_f32_e32 v105, 1.0, v105
	v_add_f32_e32 v106, 1.0, v106
	v_add_f32_e32 v107, 1.0, v107
	v_rcp_f32_e32 v108, v108
	v_rcp_f32_e32 v109, v109
	v_rcp_f32_e32 v110, v110
	v_rcp_f32_e32 v111, v111
	v_rcp_f32_e32 v104, v104
	v_rcp_f32_e32 v105, v105
	v_rcp_f32_e32 v106, v106
	v_rcp_f32_e32 v107, v107
	s_nop 0
	v_cvt_pk_bf16_f32 v108, v108, v109
	v_cvt_pk_bf16_f32 v109, v110, v111
	v_cvt_pk_bf16_f32 v110, v104, v105
	v_cvt_pk_bf16_f32 v111, v106, v107
	global_store_dwordx4 v163, v[108:111], s[30:31] sc1
	v_pk_add_f32 v[84:85], v[84:85], v[92:93]
	v_pk_add_f32 v[86:87], v[86:87], v[94:95]
	v_pk_add_f32 v[80:81], v[80:81], v[88:89]
	v_pk_add_f32 v[82:83], v[82:83], v[90:91]
	v_mul_f32_e32 v84, 0xbfb8aa3b, v84
	v_mul_f32_e32 v85, 0xbfb8aa3b, v85
	v_mul_f32_e32 v86, 0xbfb8aa3b, v86
	v_mul_f32_e32 v87, 0xbfb8aa3b, v87
	v_mul_f32_e32 v80, 0xbfb8aa3b, v80
	v_mul_f32_e32 v81, 0xbfb8aa3b, v81
	v_mul_f32_e32 v82, 0xbfb8aa3b, v82
	v_mul_f32_e32 v83, 0xbfb8aa3b, v83
	v_exp_f32_e32 v84, v84
	v_exp_f32_e32 v85, v85
	v_exp_f32_e32 v86, v86
	v_exp_f32_e32 v87, v87
	v_exp_f32_e32 v80, v80
	v_exp_f32_e32 v81, v81
	v_exp_f32_e32 v82, v82
	v_exp_f32_e32 v83, v83
	v_add_f32_e32 v84, 1.0, v84
	v_add_f32_e32 v85, 1.0, v85
	v_add_f32_e32 v86, 1.0, v86
	v_add_f32_e32 v87, 1.0, v87
	v_add_f32_e32 v80, 1.0, v80
	v_add_f32_e32 v81, 1.0, v81
	v_add_f32_e32 v82, 1.0, v82
	v_add_f32_e32 v83, 1.0, v83
	v_rcp_f32_e32 v84, v84
	v_rcp_f32_e32 v85, v85
	v_rcp_f32_e32 v86, v86
	v_rcp_f32_e32 v87, v87
	v_rcp_f32_e32 v80, v80
	v_rcp_f32_e32 v81, v81
	v_rcp_f32_e32 v82, v82
	v_rcp_f32_e32 v83, v83
	s_nop 0
	v_cvt_pk_bf16_f32 v84, v84, v85
	v_cvt_pk_bf16_f32 v85, v86, v87
	v_cvt_pk_bf16_f32 v86, v80, v81
	v_cvt_pk_bf16_f32 v87, v82, v83
	global_store_dwordx4 v164, v[84:87], s[30:31] sc1
	s_add_u32 s30, s30, s35
	s_addc_u32 s31, s31, 0
	v_pk_add_f32 v[132:133], v[132:133], v[76:77]
	v_pk_add_f32 v[134:135], v[134:135], v[78:79]
	v_pk_add_f32 v[128:129], v[128:129], v[72:73]
	v_pk_add_f32 v[130:131], v[130:131], v[74:75]
	v_mul_f32_e32 v132, 0xbfb8aa3b, v132
	v_mul_f32_e32 v133, 0xbfb8aa3b, v133
	v_mul_f32_e32 v134, 0xbfb8aa3b, v134
	v_mul_f32_e32 v135, 0xbfb8aa3b, v135
	v_mul_f32_e32 v128, 0xbfb8aa3b, v128
	v_mul_f32_e32 v129, 0xbfb8aa3b, v129
	v_mul_f32_e32 v130, 0xbfb8aa3b, v130
	v_mul_f32_e32 v131, 0xbfb8aa3b, v131
	v_exp_f32_e32 v132, v132
	v_exp_f32_e32 v133, v133
	v_exp_f32_e32 v134, v134
	v_exp_f32_e32 v135, v135
	v_exp_f32_e32 v128, v128
	v_exp_f32_e32 v129, v129
	v_exp_f32_e32 v130, v130
	v_exp_f32_e32 v131, v131
	v_add_f32_e32 v132, 1.0, v132
	v_add_f32_e32 v133, 1.0, v133
	v_add_f32_e32 v134, 1.0, v134
	v_add_f32_e32 v135, 1.0, v135
	v_add_f32_e32 v128, 1.0, v128
	v_add_f32_e32 v129, 1.0, v129
	v_add_f32_e32 v130, 1.0, v130
	v_add_f32_e32 v131, 1.0, v131
	v_rcp_f32_e32 v132, v132
	v_rcp_f32_e32 v133, v133
	v_rcp_f32_e32 v134, v134
	v_rcp_f32_e32 v135, v135
	v_rcp_f32_e32 v128, v128
	v_rcp_f32_e32 v129, v129
	v_rcp_f32_e32 v130, v130
	v_rcp_f32_e32 v131, v131
	s_nop 0
	v_cvt_pk_bf16_f32 v132, v132, v133
	v_cvt_pk_bf16_f32 v133, v134, v135
	v_cvt_pk_bf16_f32 v134, v128, v129
	v_cvt_pk_bf16_f32 v135, v130, v131
	global_store_dwordx4 v152, v[132:135], s[30:31] sc1
	v_pk_add_f32 v[116:117], v[116:117], v[76:77]
	v_pk_add_f32 v[118:119], v[118:119], v[78:79]
	v_pk_add_f32 v[112:113], v[112:113], v[72:73]
	v_pk_add_f32 v[114:115], v[114:115], v[74:75]
	v_mul_f32_e32 v116, 0xbfb8aa3b, v116
	v_mul_f32_e32 v117, 0xbfb8aa3b, v117
	v_mul_f32_e32 v118, 0xbfb8aa3b, v118
	v_mul_f32_e32 v119, 0xbfb8aa3b, v119
	v_mul_f32_e32 v112, 0xbfb8aa3b, v112
	v_mul_f32_e32 v113, 0xbfb8aa3b, v113
	v_mul_f32_e32 v114, 0xbfb8aa3b, v114
	v_mul_f32_e32 v115, 0xbfb8aa3b, v115
	v_exp_f32_e32 v116, v116
	v_exp_f32_e32 v117, v117
	v_exp_f32_e32 v118, v118
	v_exp_f32_e32 v119, v119
	v_exp_f32_e32 v112, v112
	v_exp_f32_e32 v113, v113
	v_exp_f32_e32 v114, v114
	v_exp_f32_e32 v115, v115
	v_add_f32_e32 v116, 1.0, v116
	v_add_f32_e32 v117, 1.0, v117
	v_add_f32_e32 v118, 1.0, v118
	v_add_f32_e32 v119, 1.0, v119
	v_add_f32_e32 v112, 1.0, v112
	v_add_f32_e32 v113, 1.0, v113
	v_add_f32_e32 v114, 1.0, v114
	v_add_f32_e32 v115, 1.0, v115
	v_rcp_f32_e32 v116, v116
	v_rcp_f32_e32 v117, v117
	v_rcp_f32_e32 v118, v118
	v_rcp_f32_e32 v119, v119
	v_rcp_f32_e32 v112, v112
	v_rcp_f32_e32 v113, v113
	v_rcp_f32_e32 v114, v114
	v_rcp_f32_e32 v115, v115
	s_nop 0
	v_cvt_pk_bf16_f32 v116, v116, v117
	v_cvt_pk_bf16_f32 v117, v118, v119
	v_cvt_pk_bf16_f32 v118, v112, v113
	v_cvt_pk_bf16_f32 v119, v114, v115
	global_store_dwordx4 v162, v[116:119], s[30:31] sc1
	v_pk_add_f32 v[100:101], v[100:101], v[76:77]
	v_pk_add_f32 v[102:103], v[102:103], v[78:79]
	v_pk_add_f32 v[96:97], v[96:97], v[72:73]
	v_pk_add_f32 v[98:99], v[98:99], v[74:75]
	v_mul_f32_e32 v100, 0xbfb8aa3b, v100
	v_mul_f32_e32 v101, 0xbfb8aa3b, v101
	v_mul_f32_e32 v102, 0xbfb8aa3b, v102
	v_mul_f32_e32 v103, 0xbfb8aa3b, v103
	v_mul_f32_e32 v96, 0xbfb8aa3b, v96
	v_mul_f32_e32 v97, 0xbfb8aa3b, v97
	v_mul_f32_e32 v98, 0xbfb8aa3b, v98
	v_mul_f32_e32 v99, 0xbfb8aa3b, v99
	v_exp_f32_e32 v100, v100
	v_exp_f32_e32 v101, v101
	v_exp_f32_e32 v102, v102
	v_exp_f32_e32 v103, v103
	v_exp_f32_e32 v96, v96
	v_exp_f32_e32 v97, v97
	v_exp_f32_e32 v98, v98
	v_exp_f32_e32 v99, v99
	v_add_f32_e32 v100, 1.0, v100
	v_add_f32_e32 v101, 1.0, v101
	v_add_f32_e32 v102, 1.0, v102
	v_add_f32_e32 v103, 1.0, v103
	v_add_f32_e32 v96, 1.0, v96
	v_add_f32_e32 v97, 1.0, v97
	v_add_f32_e32 v98, 1.0, v98
	v_add_f32_e32 v99, 1.0, v99
	v_rcp_f32_e32 v100, v100
	v_rcp_f32_e32 v101, v101
	v_rcp_f32_e32 v102, v102
	v_rcp_f32_e32 v103, v103
	v_rcp_f32_e32 v96, v96
	v_rcp_f32_e32 v97, v97
	v_rcp_f32_e32 v98, v98
	v_rcp_f32_e32 v99, v99
	s_nop 0
	v_cvt_pk_bf16_f32 v100, v100, v101
	v_cvt_pk_bf16_f32 v101, v102, v103
	v_cvt_pk_bf16_f32 v102, v96, v97
	v_cvt_pk_bf16_f32 v103, v98, v99
	global_store_dwordx4 v163, v[100:103], s[30:31] sc1
	v_pk_add_f32 v[68:69], v[68:69], v[76:77]
	v_pk_add_f32 v[70:71], v[70:71], v[78:79]
	v_pk_add_f32 v[64:65], v[64:65], v[72:73]
	v_pk_add_f32 v[66:67], v[66:67], v[74:75]
	v_mul_f32_e32 v68, 0xbfb8aa3b, v68
	v_mul_f32_e32 v69, 0xbfb8aa3b, v69
	v_mul_f32_e32 v70, 0xbfb8aa3b, v70
	v_mul_f32_e32 v71, 0xbfb8aa3b, v71
	v_mul_f32_e32 v64, 0xbfb8aa3b, v64
	v_mul_f32_e32 v65, 0xbfb8aa3b, v65
	v_mul_f32_e32 v66, 0xbfb8aa3b, v66
	v_mul_f32_e32 v67, 0xbfb8aa3b, v67
	v_exp_f32_e32 v68, v68
	v_exp_f32_e32 v69, v69
	v_exp_f32_e32 v70, v70
	v_exp_f32_e32 v71, v71
	v_exp_f32_e32 v64, v64
	v_exp_f32_e32 v65, v65
	v_exp_f32_e32 v66, v66
	v_exp_f32_e32 v67, v67
	v_add_f32_e32 v68, 1.0, v68
	v_add_f32_e32 v69, 1.0, v69
	v_add_f32_e32 v70, 1.0, v70
	v_add_f32_e32 v71, 1.0, v71
	v_add_f32_e32 v64, 1.0, v64
	v_add_f32_e32 v65, 1.0, v65
	v_add_f32_e32 v66, 1.0, v66
	v_add_f32_e32 v67, 1.0, v67
	v_rcp_f32_e32 v68, v68
	v_rcp_f32_e32 v69, v69
	v_rcp_f32_e32 v70, v70
	v_rcp_f32_e32 v71, v71
	v_rcp_f32_e32 v64, v64
	v_rcp_f32_e32 v65, v65
	v_rcp_f32_e32 v66, v66
	v_rcp_f32_e32 v67, v67
	s_nop 0
	v_cvt_pk_bf16_f32 v68, v68, v69
	v_cvt_pk_bf16_f32 v69, v70, v71
	v_cvt_pk_bf16_f32 v70, v64, v65
	v_cvt_pk_bf16_f32 v71, v66, v67
	global_store_dwordx4 v164, v[68:71], s[30:31] sc1
	s_sub_u32 s30, s30, s35
	s_subb_u32 s31, s31, 0
	s_add_u32 s30, s30, s5
	s_addc_u32 s31, s31, 0
	v_pk_add_f32 v[60:61], v[60:61], v[92:93]
	v_pk_add_f32 v[62:63], v[62:63], v[94:95]
	v_pk_add_f32 v[56:57], v[56:57], v[88:89]
	v_pk_add_f32 v[58:59], v[58:59], v[90:91]
	v_mul_f32_e32 v60, 0xbfb8aa3b, v60
	v_mul_f32_e32 v61, 0xbfb8aa3b, v61
	v_mul_f32_e32 v62, 0xbfb8aa3b, v62
	v_mul_f32_e32 v63, 0xbfb8aa3b, v63
	v_mul_f32_e32 v56, 0xbfb8aa3b, v56
	v_mul_f32_e32 v57, 0xbfb8aa3b, v57
	v_mul_f32_e32 v58, 0xbfb8aa3b, v58
	v_mul_f32_e32 v59, 0xbfb8aa3b, v59
	v_exp_f32_e32 v60, v60
	v_exp_f32_e32 v61, v61
	v_exp_f32_e32 v62, v62
	v_exp_f32_e32 v63, v63
	v_exp_f32_e32 v56, v56
	v_exp_f32_e32 v57, v57
	v_exp_f32_e32 v58, v58
	v_exp_f32_e32 v59, v59
	v_add_f32_e32 v60, 1.0, v60
	v_add_f32_e32 v61, 1.0, v61
	v_add_f32_e32 v62, 1.0, v62
	v_add_f32_e32 v63, 1.0, v63
	v_add_f32_e32 v56, 1.0, v56
	v_add_f32_e32 v57, 1.0, v57
	v_add_f32_e32 v58, 1.0, v58
	v_add_f32_e32 v59, 1.0, v59
	v_rcp_f32_e32 v60, v60
	v_rcp_f32_e32 v61, v61
	v_rcp_f32_e32 v62, v62
	v_rcp_f32_e32 v63, v63
	v_rcp_f32_e32 v56, v56
	v_rcp_f32_e32 v57, v57
	v_rcp_f32_e32 v58, v58
	v_rcp_f32_e32 v59, v59
	s_nop 0
	v_cvt_pk_bf16_f32 v60, v60, v61
	v_cvt_pk_bf16_f32 v61, v62, v63
	v_cvt_pk_bf16_f32 v62, v56, v57
	v_cvt_pk_bf16_f32 v63, v58, v59
	global_store_dwordx4 v152, v[60:63], s[30:31] sc1
	v_pk_add_f32 v[44:45], v[44:45], v[92:93]
	v_pk_add_f32 v[46:47], v[46:47], v[94:95]
	v_pk_add_f32 v[40:41], v[40:41], v[88:89]
	v_pk_add_f32 v[42:43], v[42:43], v[90:91]
	v_mul_f32_e32 v44, 0xbfb8aa3b, v44
	v_mul_f32_e32 v45, 0xbfb8aa3b, v45
	v_mul_f32_e32 v46, 0xbfb8aa3b, v46
	v_mul_f32_e32 v47, 0xbfb8aa3b, v47
	v_mul_f32_e32 v40, 0xbfb8aa3b, v40
	v_mul_f32_e32 v41, 0xbfb8aa3b, v41
	v_mul_f32_e32 v42, 0xbfb8aa3b, v42
	v_mul_f32_e32 v43, 0xbfb8aa3b, v43
	v_exp_f32_e32 v44, v44
	v_exp_f32_e32 v45, v45
	v_exp_f32_e32 v46, v46
	v_exp_f32_e32 v47, v47
	v_exp_f32_e32 v40, v40
	v_exp_f32_e32 v41, v41
	v_exp_f32_e32 v42, v42
	v_exp_f32_e32 v43, v43
	v_add_f32_e32 v44, 1.0, v44
	v_add_f32_e32 v45, 1.0, v45
	v_add_f32_e32 v46, 1.0, v46
	v_add_f32_e32 v47, 1.0, v47
	v_add_f32_e32 v40, 1.0, v40
	v_add_f32_e32 v41, 1.0, v41
	v_add_f32_e32 v42, 1.0, v42
	v_add_f32_e32 v43, 1.0, v43
	v_rcp_f32_e32 v44, v44
	v_rcp_f32_e32 v45, v45
	v_rcp_f32_e32 v46, v46
	v_rcp_f32_e32 v47, v47
	v_rcp_f32_e32 v40, v40
	v_rcp_f32_e32 v41, v41
	v_rcp_f32_e32 v42, v42
	v_rcp_f32_e32 v43, v43
	s_nop 0
	v_cvt_pk_bf16_f32 v44, v44, v45
	v_cvt_pk_bf16_f32 v45, v46, v47
	v_cvt_pk_bf16_f32 v46, v40, v41
	v_cvt_pk_bf16_f32 v47, v42, v43
	global_store_dwordx4 v162, v[44:47], s[30:31] sc1
	v_pk_add_f32 v[28:29], v[28:29], v[92:93]
	v_pk_add_f32 v[30:31], v[30:31], v[94:95]
	v_pk_add_f32 v[24:25], v[24:25], v[88:89]
	v_pk_add_f32 v[26:27], v[26:27], v[90:91]
	v_mul_f32_e32 v28, 0xbfb8aa3b, v28
	v_mul_f32_e32 v29, 0xbfb8aa3b, v29
	v_mul_f32_e32 v30, 0xbfb8aa3b, v30
	v_mul_f32_e32 v31, 0xbfb8aa3b, v31
	v_mul_f32_e32 v24, 0xbfb8aa3b, v24
	v_mul_f32_e32 v25, 0xbfb8aa3b, v25
	v_mul_f32_e32 v26, 0xbfb8aa3b, v26
	v_mul_f32_e32 v27, 0xbfb8aa3b, v27
	v_exp_f32_e32 v28, v28
	v_exp_f32_e32 v29, v29
	v_exp_f32_e32 v30, v30
	v_exp_f32_e32 v31, v31
	v_exp_f32_e32 v24, v24
	v_exp_f32_e32 v25, v25
	v_exp_f32_e32 v26, v26
	v_exp_f32_e32 v27, v27
	v_add_f32_e32 v28, 1.0, v28
	v_add_f32_e32 v29, 1.0, v29
	v_add_f32_e32 v30, 1.0, v30
	v_add_f32_e32 v31, 1.0, v31
	v_add_f32_e32 v24, 1.0, v24
	v_add_f32_e32 v25, 1.0, v25
	v_add_f32_e32 v26, 1.0, v26
	v_add_f32_e32 v27, 1.0, v27
	v_rcp_f32_e32 v28, v28
	v_rcp_f32_e32 v29, v29
	v_rcp_f32_e32 v30, v30
	v_rcp_f32_e32 v31, v31
	v_rcp_f32_e32 v24, v24
	v_rcp_f32_e32 v25, v25
	v_rcp_f32_e32 v26, v26
	v_rcp_f32_e32 v27, v27
	s_nop 0
	v_cvt_pk_bf16_f32 v28, v28, v29
	v_cvt_pk_bf16_f32 v29, v30, v31
	v_cvt_pk_bf16_f32 v30, v24, v25
	v_cvt_pk_bf16_f32 v31, v26, v27
	global_store_dwordx4 v163, v[28:31], s[30:31] sc1
	v_pk_add_f32 v[12:13], v[12:13], v[92:93]
	v_pk_add_f32 v[14:15], v[14:15], v[94:95]
	v_pk_add_f32 v[8:9], v[8:9], v[88:89]
	v_pk_add_f32 v[10:11], v[10:11], v[90:91]
	v_mul_f32_e32 v12, 0xbfb8aa3b, v12
	v_mul_f32_e32 v13, 0xbfb8aa3b, v13
	v_mul_f32_e32 v14, 0xbfb8aa3b, v14
	v_mul_f32_e32 v15, 0xbfb8aa3b, v15
	v_mul_f32_e32 v8, 0xbfb8aa3b, v8
	v_mul_f32_e32 v9, 0xbfb8aa3b, v9
	v_mul_f32_e32 v10, 0xbfb8aa3b, v10
	v_mul_f32_e32 v11, 0xbfb8aa3b, v11
	v_exp_f32_e32 v12, v12
	v_exp_f32_e32 v13, v13
	v_exp_f32_e32 v14, v14
	v_exp_f32_e32 v15, v15
	v_exp_f32_e32 v8, v8
	v_exp_f32_e32 v9, v9
	v_exp_f32_e32 v10, v10
	v_exp_f32_e32 v11, v11
	v_add_f32_e32 v12, 1.0, v12
	v_add_f32_e32 v13, 1.0, v13
	v_add_f32_e32 v14, 1.0, v14
	v_add_f32_e32 v15, 1.0, v15
	v_add_f32_e32 v8, 1.0, v8
	v_add_f32_e32 v9, 1.0, v9
	v_add_f32_e32 v10, 1.0, v10
	v_add_f32_e32 v11, 1.0, v11
	v_rcp_f32_e32 v12, v12
	v_rcp_f32_e32 v13, v13
	v_rcp_f32_e32 v14, v14
	v_rcp_f32_e32 v15, v15
	v_rcp_f32_e32 v8, v8
	v_rcp_f32_e32 v9, v9
	v_rcp_f32_e32 v10, v10
	v_rcp_f32_e32 v11, v11
	s_nop 0
	v_cvt_pk_bf16_f32 v12, v12, v13
	v_cvt_pk_bf16_f32 v13, v14, v15
	v_cvt_pk_bf16_f32 v14, v8, v9
	v_cvt_pk_bf16_f32 v15, v10, v11
	global_store_dwordx4 v164, v[12:15], s[30:31] sc1
	s_add_u32 s30, s30, s35
	s_addc_u32 s31, s31, 0
	v_pk_add_f32 v[52:53], v[52:53], v[76:77]
	v_pk_add_f32 v[54:55], v[54:55], v[78:79]
	v_pk_add_f32 v[48:49], v[48:49], v[72:73]
	v_pk_add_f32 v[50:51], v[50:51], v[74:75]
	v_mul_f32_e32 v52, 0xbfb8aa3b, v52
	v_mul_f32_e32 v53, 0xbfb8aa3b, v53
	v_mul_f32_e32 v54, 0xbfb8aa3b, v54
	v_mul_f32_e32 v55, 0xbfb8aa3b, v55
	v_mul_f32_e32 v48, 0xbfb8aa3b, v48
	v_mul_f32_e32 v49, 0xbfb8aa3b, v49
	v_mul_f32_e32 v50, 0xbfb8aa3b, v50
	v_mul_f32_e32 v51, 0xbfb8aa3b, v51
	v_exp_f32_e32 v52, v52
	v_exp_f32_e32 v53, v53
	v_exp_f32_e32 v54, v54
	v_exp_f32_e32 v55, v55
	v_exp_f32_e32 v48, v48
	v_exp_f32_e32 v49, v49
	v_exp_f32_e32 v50, v50
	v_exp_f32_e32 v51, v51
	v_add_f32_e32 v52, 1.0, v52
	v_add_f32_e32 v53, 1.0, v53
	v_add_f32_e32 v54, 1.0, v54
	v_add_f32_e32 v55, 1.0, v55
	v_add_f32_e32 v48, 1.0, v48
	v_add_f32_e32 v49, 1.0, v49
	v_add_f32_e32 v50, 1.0, v50
	v_add_f32_e32 v51, 1.0, v51
	v_rcp_f32_e32 v52, v52
	v_rcp_f32_e32 v53, v53
	v_rcp_f32_e32 v54, v54
	v_rcp_f32_e32 v55, v55
	v_rcp_f32_e32 v48, v48
	v_rcp_f32_e32 v49, v49
	v_rcp_f32_e32 v50, v50
	v_rcp_f32_e32 v51, v51
	s_nop 0
	v_cvt_pk_bf16_f32 v52, v52, v53
	v_cvt_pk_bf16_f32 v53, v54, v55
	v_cvt_pk_bf16_f32 v54, v48, v49
	v_cvt_pk_bf16_f32 v55, v50, v51
	global_store_dwordx4 v152, v[52:55], s[30:31] sc1
	v_pk_add_f32 v[36:37], v[36:37], v[76:77]
	v_pk_add_f32 v[38:39], v[38:39], v[78:79]
	v_pk_add_f32 v[32:33], v[32:33], v[72:73]
	v_pk_add_f32 v[34:35], v[34:35], v[74:75]
	v_mul_f32_e32 v36, 0xbfb8aa3b, v36
	v_mul_f32_e32 v37, 0xbfb8aa3b, v37
	v_mul_f32_e32 v38, 0xbfb8aa3b, v38
	v_mul_f32_e32 v39, 0xbfb8aa3b, v39
	v_mul_f32_e32 v32, 0xbfb8aa3b, v32
	v_mul_f32_e32 v33, 0xbfb8aa3b, v33
	v_mul_f32_e32 v34, 0xbfb8aa3b, v34
	v_mul_f32_e32 v35, 0xbfb8aa3b, v35
	v_exp_f32_e32 v36, v36
	v_exp_f32_e32 v37, v37
	v_exp_f32_e32 v38, v38
	v_exp_f32_e32 v39, v39
	v_exp_f32_e32 v32, v32
	v_exp_f32_e32 v33, v33
	v_exp_f32_e32 v34, v34
	v_exp_f32_e32 v35, v35
	v_add_f32_e32 v36, 1.0, v36
	v_add_f32_e32 v37, 1.0, v37
	v_add_f32_e32 v38, 1.0, v38
	v_add_f32_e32 v39, 1.0, v39
	v_add_f32_e32 v32, 1.0, v32
	v_add_f32_e32 v33, 1.0, v33
	v_add_f32_e32 v34, 1.0, v34
	v_add_f32_e32 v35, 1.0, v35
	v_rcp_f32_e32 v36, v36
	v_rcp_f32_e32 v37, v37
	v_rcp_f32_e32 v38, v38
	v_rcp_f32_e32 v39, v39
	v_rcp_f32_e32 v32, v32
	v_rcp_f32_e32 v33, v33
	v_rcp_f32_e32 v34, v34
	v_rcp_f32_e32 v35, v35
	s_nop 0
	v_cvt_pk_bf16_f32 v36, v36, v37
	v_cvt_pk_bf16_f32 v37, v38, v39
	v_cvt_pk_bf16_f32 v38, v32, v33
	v_cvt_pk_bf16_f32 v39, v34, v35
	global_store_dwordx4 v162, v[36:39], s[30:31] sc1
	v_pk_add_f32 v[20:21], v[20:21], v[76:77]
	v_pk_add_f32 v[22:23], v[22:23], v[78:79]
	v_pk_add_f32 v[16:17], v[16:17], v[72:73]
	v_pk_add_f32 v[18:19], v[18:19], v[74:75]
	v_mul_f32_e32 v20, 0xbfb8aa3b, v20
	v_mul_f32_e32 v21, 0xbfb8aa3b, v21
	v_mul_f32_e32 v22, 0xbfb8aa3b, v22
	v_mul_f32_e32 v23, 0xbfb8aa3b, v23
	v_mul_f32_e32 v16, 0xbfb8aa3b, v16
	v_mul_f32_e32 v17, 0xbfb8aa3b, v17
	v_mul_f32_e32 v18, 0xbfb8aa3b, v18
	v_mul_f32_e32 v19, 0xbfb8aa3b, v19
	v_exp_f32_e32 v20, v20
	v_exp_f32_e32 v21, v21
	v_exp_f32_e32 v22, v22
	v_exp_f32_e32 v23, v23
	v_exp_f32_e32 v16, v16
	v_exp_f32_e32 v17, v17
	v_exp_f32_e32 v18, v18
	v_exp_f32_e32 v19, v19
	v_add_f32_e32 v20, 1.0, v20
	v_add_f32_e32 v21, 1.0, v21
	v_add_f32_e32 v22, 1.0, v22
	v_add_f32_e32 v23, 1.0, v23
	v_add_f32_e32 v16, 1.0, v16
	v_add_f32_e32 v17, 1.0, v17
	v_add_f32_e32 v18, 1.0, v18
	v_add_f32_e32 v19, 1.0, v19
	v_rcp_f32_e32 v20, v20
	v_rcp_f32_e32 v21, v21
	v_rcp_f32_e32 v22, v22
	v_rcp_f32_e32 v23, v23
	v_rcp_f32_e32 v16, v16
	v_rcp_f32_e32 v17, v17
	v_rcp_f32_e32 v18, v18
	v_rcp_f32_e32 v19, v19
	s_nop 0
	v_cvt_pk_bf16_f32 v20, v20, v21
	v_cvt_pk_bf16_f32 v21, v22, v23
	v_cvt_pk_bf16_f32 v22, v16, v17
	v_cvt_pk_bf16_f32 v23, v18, v19
	global_store_dwordx4 v163, v[20:23], s[30:31] sc1
	v_pk_add_f32 v[4:5], v[4:5], v[76:77]
	v_pk_add_f32 v[6:7], v[6:7], v[78:79]
	v_pk_add_f32 v[0:1], v[0:1], v[72:73]
	v_pk_add_f32 v[2:3], v[2:3], v[74:75]
	v_mul_f32_e32 v4, 0xbfb8aa3b, v4
	v_mul_f32_e32 v5, 0xbfb8aa3b, v5
	v_mul_f32_e32 v6, 0xbfb8aa3b, v6
	v_mul_f32_e32 v7, 0xbfb8aa3b, v7
	v_mul_f32_e32 v0, 0xbfb8aa3b, v0
	v_mul_f32_e32 v1, 0xbfb8aa3b, v1
	v_mul_f32_e32 v2, 0xbfb8aa3b, v2
	v_mul_f32_e32 v3, 0xbfb8aa3b, v3
	v_exp_f32_e32 v4, v4
	v_exp_f32_e32 v5, v5
	v_exp_f32_e32 v6, v6
	v_exp_f32_e32 v7, v7
	v_exp_f32_e32 v0, v0
	v_exp_f32_e32 v1, v1
	v_exp_f32_e32 v2, v2
	v_exp_f32_e32 v3, v3
	v_add_f32_e32 v4, 1.0, v4
	v_add_f32_e32 v5, 1.0, v5
	v_add_f32_e32 v6, 1.0, v6
	v_add_f32_e32 v7, 1.0, v7
	v_add_f32_e32 v0, 1.0, v0
	v_add_f32_e32 v1, 1.0, v1
	v_add_f32_e32 v2, 1.0, v2
	v_add_f32_e32 v3, 1.0, v3
	v_rcp_f32_e32 v4, v4
	v_rcp_f32_e32 v5, v5
	v_rcp_f32_e32 v6, v6
	v_rcp_f32_e32 v7, v7
	v_rcp_f32_e32 v0, v0
	v_rcp_f32_e32 v1, v1
	v_rcp_f32_e32 v2, v2
	v_rcp_f32_e32 v3, v3
	s_nop 0
	v_cvt_pk_bf16_f32 v4, v4, v5
	v_cvt_pk_bf16_f32 v5, v6, v7
	v_cvt_pk_bf16_f32 v6, v0, v1
	v_cvt_pk_bf16_f32 v7, v2, v3
	global_store_dwordx4 v164, v[4:7], s[30:31] sc1
